# stack of all validated edits: v073 (tile-start restructure + barrier waiters poll arrival counter) + counted-wait ladder in final FFN-out epilogue
# baseline (speedup 1.0000x reference)
.LBB0_1276:
	v_mov_b32_e32 v128, v194
	v_mov_b32_e32 v129, v195
	s_lshl_b32 s16, s43, 8
	s_add_i32 s16, s16, s31
	v_add_u32_e32 v128, s16, v128
	s_lshl_b32 s16, s42, 8
	s_or_b32 s16, s16, s34
	v_lshl_add_u32 v130, v129, 3, s16
	v_ashrrev_i32_e32 v131, 31, v130
	v_ashrrev_i32_e32 v129, 31, v128
	v_lshl_add_u64 v[132:133], v[130:131], 1, s[58:59]
	v_lshlrev_b64 v[134:135], 11, v[128:129]
	v_add_u32_e32 v228, 16, v128
	v_lshl_add_u64 v[134:135], v[132:133], 0, v[134:135]
	v_ashrrev_i32_e32 v229, 31, v228
	global_load_dwordx4 v[200:203], v[134:135], off
	global_load_dwordx4 v[204:207], v[134:135], off offset:256
	v_lshlrev_b64 v[134:135], 11, v[228:229]
	v_lshl_add_u64 v[134:135], v[132:133], 0, v[134:135]
	global_load_dwordx4 v[208:211], v[134:135], off
	v_add_u32_e32 v192, 32, v128
	v_ashrrev_i32_e32 v193, 31, v192
	global_load_dwordx4 v[212:215], v[134:135], off offset:256
	v_lshlrev_b64 v[182:183], 2, v[130:131]
	v_lshlrev_b64 v[130:131], 11, v[192:193]
	v_lshl_add_u64 v[130:131], v[132:133], 0, v[130:131]
	global_load_dwordx4 v[216:219], v[130:131], off
	v_add_u32_e32 v190, 48, v128
	v_add_u32_e32 v188, 0x80, v128
	v_add_u32_e32 v186, 0x90, v128
	v_add_u32_e32 v184, 0xa0, v128
	v_add_u32_e32 v180, 0xb0, v128
	v_ashrrev_i32_e32 v191, 31, v190
	v_ashrrev_i32_e32 v189, 31, v188
	v_ashrrev_i32_e32 v187, 31, v186
	v_ashrrev_i32_e32 v185, 31, v184
	v_ashrrev_i32_e32 v181, 31, v180
	v_lshlrev_b64 v[128:129], 12, v[128:129]
	v_lshlrev_b64 v[134:135], 11, v[190:191]
	v_lshlrev_b64 v[136:137], 11, v[188:189]
	v_lshlrev_b64 v[138:139], 11, v[186:187]
	v_lshlrev_b64 v[140:141], 11, v[184:185]
	v_lshlrev_b64 v[142:143], 11, v[180:181]
	v_lshl_add_u64 v[128:129], s[6:7], 0, v[128:129]
	v_lshl_add_u64 v[134:135], v[132:133], 0, v[134:135]
	v_lshl_add_u64 v[136:137], v[132:133], 0, v[136:137]
	v_lshl_add_u64 v[138:139], v[132:133], 0, v[138:139]
	v_lshl_add_u64 v[230:231], v[132:133], 0, v[140:141]
	v_lshl_add_u64 v[232:233], v[132:133], 0, v[142:143]
	v_lshl_add_u64 v[234:235], v[128:129], 0, v[182:183]
	global_load_dwordx4 v[220:223], v[130:131], off offset:256
	global_load_dwordx4 v[224:227], v[134:135], off
	global_load_dwordx4 v[160:163], v[134:135], off offset:256
	global_load_dwordx4 v[156:159], v[136:137], off
	global_load_dwordx4 v[152:155], v[136:137], off offset:256
	global_load_dwordx4 v[148:151], v[138:139], off
	global_load_dwordx4 v[144:147], v[138:139], off offset:256
	global_load_dwordx4 v[140:143], v[230:231], off
	s_nop 0
	global_load_dwordx4 v[136:139], v[230:231], off offset:256
	global_load_dwordx4 v[132:135], v[232:233], off
	global_load_dwordx4 v[128:131], v[232:233], off offset:256
	s_and_b64 vcc, exec, s[0:1]
	s_mov_b64 s[0:1], -1
	s_waitcnt vmcnt(15)
	v_lshlrev_b32_e32 v230, 16, v200
	v_and_b32_e32 v231, 0xffff0000, v200
	v_lshlrev_b32_e32 v200, 16, v201
	v_and_b32_e32 v201, 0xffff0000, v201
	s_waitcnt vmcnt(14)
	v_lshlrev_b32_e32 v238, 16, v206
	v_and_b32_e32 v239, 0xffff0000, v206
	v_lshlrev_b32_e32 v232, 16, v202
	v_and_b32_e32 v233, 0xffff0000, v202
	v_lshlrev_b32_e32 v202, 16, v203
	v_and_b32_e32 v203, 0xffff0000, v203
	v_lshlrev_b32_e32 v236, 16, v204
	v_and_b32_e32 v237, 0xffff0000, v204
	v_lshlrev_b32_e32 v204, 16, v205
	v_and_b32_e32 v205, 0xffff0000, v205
	v_lshlrev_b32_e32 v206, 16, v207
	v_and_b32_e32 v207, 0xffff0000, v207
	v_pk_add_f32 v[126:127], v[126:127], v[200:201]
	v_pk_add_f32 v[124:125], v[124:125], v[230:231]
	v_pk_add_f32 v[108:109], v[108:109], v[238:239]
	v_pk_add_f32 v[122:123], v[122:123], v[202:203]
	v_pk_add_f32 v[120:121], v[120:121], v[232:233]
	v_pk_add_f32 v[118:119], v[118:119], v[204:205]
	v_pk_add_f32 v[116:117], v[116:117], v[236:237]
	v_pk_add_f32 v[110:111], v[110:111], v[206:207]
	global_store_dwordx4 v[234:235], v[124:127], off nt
	global_store_dwordx4 v[234:235], v[120:123], off offset:16 nt
	global_store_dwordx4 v[234:235], v[116:119], off offset:512 nt
	global_store_dwordx4 v[234:235], v[108:111], off offset:528 nt
	s_nop 0
	s_waitcnt vmcnt(17)
	v_lshlrev_b32_e32 v116, 16, v210
	v_lshlrev_b32_e32 v108, 16, v208
	v_and_b32_e32 v109, 0xffff0000, v208
	v_pk_add_f32 v[108:109], v[112:113], v[108:109]
	v_lshlrev_b64 v[112:113], 12, v[228:229]
	v_lshlrev_b32_e32 v110, 16, v209
	v_and_b32_e32 v111, 0xffff0000, v209
	v_and_b32_e32 v117, 0xffff0000, v210
	v_lshlrev_b32_e32 v118, 16, v211
	v_and_b32_e32 v119, 0xffff0000, v211
	v_lshl_add_u64 v[112:113], s[6:7], 0, v[112:113]
	v_pk_add_f32 v[110:111], v[114:115], v[110:111]
	v_pk_add_f32 v[106:107], v[106:107], v[118:119]
	v_pk_add_f32 v[104:105], v[104:105], v[116:117]
	v_lshl_add_u64 v[112:113], v[112:113], 0, v[182:183]
	global_store_dwordx4 v[112:113], v[108:111], off nt
	global_store_dwordx4 v[112:113], v[104:107], off offset:16 nt
	s_nop 0
	s_waitcnt vmcnt(18)
	v_lshlrev_b32_e32 v108, 16, v214
	v_lshlrev_b32_e32 v104, 16, v212
	v_and_b32_e32 v105, 0xffff0000, v212
	v_lshlrev_b32_e32 v106, 16, v213
	v_and_b32_e32 v107, 0xffff0000, v213
	v_and_b32_e32 v109, 0xffff0000, v214
	v_lshlrev_b32_e32 v110, 16, v215
	v_and_b32_e32 v111, 0xffff0000, v215
	v_pk_add_f32 v[102:103], v[102:103], v[106:107]
	v_pk_add_f32 v[100:101], v[100:101], v[104:105]
	v_pk_add_f32 v[92:93], v[92:93], v[108:109]
	v_pk_add_f32 v[94:95], v[94:95], v[110:111]
	global_store_dwordx4 v[112:113], v[100:103], off offset:512 nt
	global_store_dwordx4 v[112:113], v[92:95], off offset:528 nt
	s_nop 0
	s_waitcnt vmcnt(19)
	v_lshlrev_b32_e32 v100, 16, v218
	v_lshlrev_b32_e32 v92, 16, v216
	v_and_b32_e32 v93, 0xffff0000, v216
	v_pk_add_f32 v[92:93], v[96:97], v[92:93]
	v_lshlrev_b64 v[96:97], 12, v[192:193]
	v_lshlrev_b32_e32 v94, 16, v217
	v_and_b32_e32 v95, 0xffff0000, v217
	v_and_b32_e32 v101, 0xffff0000, v218
	v_lshlrev_b32_e32 v102, 16, v219
	v_and_b32_e32 v103, 0xffff0000, v219
	v_lshl_add_u64 v[96:97], s[6:7], 0, v[96:97]
	v_pk_add_f32 v[94:95], v[98:99], v[94:95]
	v_pk_add_f32 v[90:91], v[90:91], v[102:103]
	v_pk_add_f32 v[88:89], v[88:89], v[100:101]
	v_lshl_add_u64 v[96:97], v[96:97], 0, v[182:183]
	global_store_dwordx4 v[96:97], v[92:95], off nt
	global_store_dwordx4 v[96:97], v[88:91], off offset:16 nt
	s_nop 0
	s_waitcnt vmcnt(20)
	v_lshlrev_b32_e32 v92, 16, v222
	v_lshlrev_b32_e32 v88, 16, v220
	v_and_b32_e32 v89, 0xffff0000, v220
	v_lshlrev_b32_e32 v90, 16, v221
	v_and_b32_e32 v91, 0xffff0000, v221
	v_and_b32_e32 v93, 0xffff0000, v222
	v_lshlrev_b32_e32 v94, 16, v223
	v_and_b32_e32 v95, 0xffff0000, v223
	v_pk_add_f32 v[86:87], v[86:87], v[90:91]
	v_pk_add_f32 v[84:85], v[84:85], v[88:89]
	v_pk_add_f32 v[76:77], v[76:77], v[92:93]
	v_pk_add_f32 v[78:79], v[78:79], v[94:95]
	global_store_dwordx4 v[96:97], v[84:87], off offset:512 nt
	global_store_dwordx4 v[96:97], v[76:79], off offset:528 nt
	s_nop 0
	s_waitcnt vmcnt(21)
	v_lshlrev_b32_e32 v84, 16, v226
	v_lshlrev_b32_e32 v76, 16, v224
	v_and_b32_e32 v77, 0xffff0000, v224
	v_pk_add_f32 v[76:77], v[80:81], v[76:77]
	v_lshlrev_b64 v[80:81], 12, v[190:191]
	v_lshlrev_b32_e32 v78, 16, v225
	v_and_b32_e32 v79, 0xffff0000, v225
	v_and_b32_e32 v85, 0xffff0000, v226
	v_lshlrev_b32_e32 v86, 16, v227
	v_and_b32_e32 v87, 0xffff0000, v227
	v_lshl_add_u64 v[80:81], s[6:7], 0, v[80:81]
	v_pk_add_f32 v[78:79], v[82:83], v[78:79]
	v_pk_add_f32 v[74:75], v[74:75], v[86:87]
	v_pk_add_f32 v[72:73], v[72:73], v[84:85]
	v_lshl_add_u64 v[80:81], v[80:81], 0, v[182:183]
	global_store_dwordx4 v[80:81], v[76:79], off nt
	global_store_dwordx4 v[80:81], v[72:75], off offset:16 nt
	s_nop 0
	s_waitcnt vmcnt(22)
	v_lshlrev_b32_e32 v76, 16, v162
	v_lshlrev_b32_e32 v72, 16, v160
	v_and_b32_e32 v73, 0xffff0000, v160
	v_lshlrev_b32_e32 v74, 16, v161
	v_and_b32_e32 v75, 0xffff0000, v161
	v_and_b32_e32 v77, 0xffff0000, v162
	v_lshlrev_b32_e32 v78, 16, v163
	v_and_b32_e32 v79, 0xffff0000, v163
	v_pk_add_f32 v[70:71], v[70:71], v[74:75]
	v_pk_add_f32 v[68:69], v[68:69], v[72:73]
	v_pk_add_f32 v[64:65], v[64:65], v[76:77]
	v_pk_add_f32 v[66:67], v[66:67], v[78:79]
	global_store_dwordx4 v[80:81], v[68:71], off offset:512 nt
	global_store_dwordx4 v[80:81], v[64:67], off offset:528 nt
	s_nop 0
	s_waitcnt vmcnt(23)
	v_lshlrev_b32_e32 v68, 16, v158
	v_lshlrev_b32_e32 v64, 16, v156
	v_and_b32_e32 v65, 0xffff0000, v156
	v_pk_add_f32 v[60:61], v[60:61], v[64:65]
	v_lshlrev_b64 v[64:65], 12, v[188:189]
	v_lshlrev_b32_e32 v66, 16, v157
	v_and_b32_e32 v67, 0xffff0000, v157
	v_and_b32_e32 v69, 0xffff0000, v158
	v_lshlrev_b32_e32 v70, 16, v159
	v_and_b32_e32 v71, 0xffff0000, v159
	v_lshl_add_u64 v[64:65], s[6:7], 0, v[64:65]
	v_pk_add_f32 v[62:63], v[62:63], v[66:67]
	v_pk_add_f32 v[58:59], v[58:59], v[70:71]
	v_pk_add_f32 v[56:57], v[56:57], v[68:69]
	v_lshl_add_u64 v[64:65], v[64:65], 0, v[182:183]
	global_store_dwordx4 v[64:65], v[60:63], off nt
	global_store_dwordx4 v[64:65], v[56:59], off offset:16 nt
	s_nop 0
	s_waitcnt vmcnt(24)
	v_lshlrev_b32_e32 v60, 16, v154
	v_lshlrev_b32_e32 v56, 16, v152
	v_and_b32_e32 v57, 0xffff0000, v152
	v_lshlrev_b32_e32 v58, 16, v153
	v_and_b32_e32 v59, 0xffff0000, v153
	v_and_b32_e32 v61, 0xffff0000, v154
	v_lshlrev_b32_e32 v62, 16, v155
	v_and_b32_e32 v63, 0xffff0000, v155
	v_pk_add_f32 v[54:55], v[54:55], v[58:59]
	v_pk_add_f32 v[52:53], v[52:53], v[56:57]
	v_pk_add_f32 v[44:45], v[44:45], v[60:61]
	v_pk_add_f32 v[46:47], v[46:47], v[62:63]
	global_store_dwordx4 v[64:65], v[52:55], off offset:512 nt
	global_store_dwordx4 v[64:65], v[44:47], off offset:528 nt
	s_nop 0
	s_waitcnt vmcnt(25)
	v_lshlrev_b32_e32 v52, 16, v150
	v_lshlrev_b32_e32 v44, 16, v148
	v_and_b32_e32 v45, 0xffff0000, v148
	v_pk_add_f32 v[44:45], v[48:49], v[44:45]
	v_lshlrev_b64 v[48:49], 12, v[186:187]
	v_lshlrev_b32_e32 v46, 16, v149
	v_and_b32_e32 v47, 0xffff0000, v149
	v_and_b32_e32 v53, 0xffff0000, v150
	v_lshlrev_b32_e32 v54, 16, v151
	v_and_b32_e32 v55, 0xffff0000, v151
	v_lshl_add_u64 v[48:49], s[6:7], 0, v[48:49]
	v_pk_add_f32 v[46:47], v[50:51], v[46:47]
	v_pk_add_f32 v[42:43], v[42:43], v[54:55]
	v_pk_add_f32 v[40:41], v[40:41], v[52:53]
	v_lshl_add_u64 v[48:49], v[48:49], 0, v[182:183]
	global_store_dwordx4 v[48:49], v[44:47], off nt
	global_store_dwordx4 v[48:49], v[40:43], off offset:16 nt
	s_nop 0
	s_waitcnt vmcnt(26)
	v_lshlrev_b32_e32 v44, 16, v146
	v_lshlrev_b32_e32 v40, 16, v144
	v_and_b32_e32 v41, 0xffff0000, v144
	v_lshlrev_b32_e32 v42, 16, v145
	v_and_b32_e32 v43, 0xffff0000, v145
	v_and_b32_e32 v45, 0xffff0000, v146
	v_lshlrev_b32_e32 v46, 16, v147
	v_and_b32_e32 v47, 0xffff0000, v147
	v_pk_add_f32 v[38:39], v[38:39], v[42:43]
	v_pk_add_f32 v[36:37], v[36:37], v[40:41]
	v_pk_add_f32 v[28:29], v[28:29], v[44:45]
	v_pk_add_f32 v[30:31], v[30:31], v[46:47]
	global_store_dwordx4 v[48:49], v[36:39], off offset:512 nt
	global_store_dwordx4 v[48:49], v[28:31], off offset:528 nt
	s_nop 0
	s_waitcnt vmcnt(27)
	v_lshlrev_b32_e32 v36, 16, v142
	v_lshlrev_b32_e32 v28, 16, v140
	v_and_b32_e32 v29, 0xffff0000, v140
	v_pk_add_f32 v[28:29], v[32:33], v[28:29]
	v_lshlrev_b64 v[32:33], 12, v[184:185]
	v_lshlrev_b32_e32 v30, 16, v141
	v_and_b32_e32 v31, 0xffff0000, v141
	v_and_b32_e32 v37, 0xffff0000, v142
	v_lshlrev_b32_e32 v38, 16, v143
	v_and_b32_e32 v39, 0xffff0000, v143
	v_lshl_add_u64 v[32:33], s[6:7], 0, v[32:33]
	v_pk_add_f32 v[30:31], v[34:35], v[30:31]
	v_pk_add_f32 v[26:27], v[26:27], v[38:39]
	v_pk_add_f32 v[24:25], v[24:25], v[36:37]
	v_lshl_add_u64 v[32:33], v[32:33], 0, v[182:183]
	global_store_dwordx4 v[32:33], v[28:31], off nt
	global_store_dwordx4 v[32:33], v[24:27], off offset:16 nt
	s_nop 0
	s_waitcnt vmcnt(28)
	v_lshlrev_b32_e32 v28, 16, v138
	v_lshlrev_b32_e32 v24, 16, v136
	v_and_b32_e32 v25, 0xffff0000, v136
	v_lshlrev_b32_e32 v26, 16, v137
	v_and_b32_e32 v27, 0xffff0000, v137
	v_and_b32_e32 v29, 0xffff0000, v138
	v_lshlrev_b32_e32 v30, 16, v139
	v_and_b32_e32 v31, 0xffff0000, v139
	v_pk_add_f32 v[22:23], v[22:23], v[26:27]
	v_pk_add_f32 v[20:21], v[20:21], v[24:25]
	v_pk_add_f32 v[12:13], v[12:13], v[28:29]
	v_pk_add_f32 v[14:15], v[14:15], v[30:31]
	global_store_dwordx4 v[32:33], v[20:23], off offset:512 nt
	global_store_dwordx4 v[32:33], v[12:15], off offset:528 nt
	s_nop 0
	s_waitcnt vmcnt(29)
	v_lshlrev_b32_e32 v20, 16, v134
	v_lshlrev_b32_e32 v12, 16, v132
	v_and_b32_e32 v13, 0xffff0000, v132
	v_pk_add_f32 v[12:13], v[16:17], v[12:13]
	v_lshlrev_b64 v[16:17], 12, v[180:181]
	v_lshlrev_b32_e32 v14, 16, v133
	v_and_b32_e32 v15, 0xffff0000, v133
	v_and_b32_e32 v21, 0xffff0000, v134
	v_lshlrev_b32_e32 v22, 16, v135
	v_and_b32_e32 v23, 0xffff0000, v135
	v_lshl_add_u64 v[16:17], s[6:7], 0, v[16:17]
	v_pk_add_f32 v[14:15], v[18:19], v[14:15]
	v_pk_add_f32 v[10:11], v[10:11], v[22:23]
	v_pk_add_f32 v[8:9], v[8:9], v[20:21]
	v_lshl_add_u64 v[16:17], v[16:17], 0, v[182:183]
	global_store_dwordx4 v[16:17], v[12:15], off nt
	global_store_dwordx4 v[16:17], v[8:11], off offset:16 nt
	s_nop 0
	s_waitcnt vmcnt(30)
	v_lshlrev_b32_e32 v12, 16, v130
	v_lshlrev_b32_e32 v8, 16, v128
	v_and_b32_e32 v9, 0xffff0000, v128
	v_lshlrev_b32_e32 v10, 16, v129
	v_and_b32_e32 v11, 0xffff0000, v129
	v_and_b32_e32 v13, 0xffff0000, v130
	v_lshlrev_b32_e32 v14, 16, v131
	v_and_b32_e32 v15, 0xffff0000, v131
	v_pk_add_f32 v[6:7], v[6:7], v[10:11]
	v_pk_add_f32 v[4:5], v[4:5], v[8:9]
	v_pk_add_f32 v[2:3], v[2:3], v[14:15]
	v_pk_add_f32 v[0:1], v[0:1], v[12:13]
	global_store_dwordx4 v[16:17], v[4:7], off offset:512 nt
	global_store_dwordx4 v[16:17], v[0:3], off offset:528 nt
	s_cbranch_vccnz .LBB0_1261
	s_mov_b32 s101, 0
	s_andn2_b64 vcc, exec, s[8:9]
	s_cbranch_vccnz .LBB0_1260
	s_mov_b32 s101, 1
	s_branch .LBB0_1260
